# c6_mla_fastpath_v2
# speedup vs baseline: 1.0126x; 1.0126x over previous
.Lfm_odd_exp:
	v_sub_f32_e32 v96, v112, v236
	v_sub_f32_e32 v80, v128, v236
	v_sub_f32_e32 v97, v113, v236
	v_sub_f32_e32 v81, v129, v236
	v_sub_f32_e32 v98, v114, v236
	v_sub_f32_e32 v82, v130, v236
	v_sub_f32_e32 v99, v115, v236
	v_sub_f32_e32 v83, v131, v236
	v_sub_f32_e32 v100, v116, v236
	v_sub_f32_e32 v84, v132, v236
	v_sub_f32_e32 v101, v117, v236
	v_sub_f32_e32 v85, v133, v236
	v_sub_f32_e32 v102, v118, v236
	v_sub_f32_e32 v86, v134, v236
	v_sub_f32_e32 v103, v119, v236
	v_sub_f32_e32 v87, v135, v236
	v_sub_f32_e32 v104, v120, v236
	v_sub_f32_e32 v88, v136, v236
	v_sub_f32_e32 v105, v121, v236
	v_sub_f32_e32 v89, v137, v236
	v_sub_f32_e32 v106, v122, v236
	v_sub_f32_e32 v90, v138, v236
	v_sub_f32_e32 v107, v123, v236
	v_sub_f32_e32 v91, v139, v236
	v_sub_f32_e32 v108, v124, v236
	v_sub_f32_e32 v92, v140, v236
	v_sub_f32_e32 v109, v125, v236
	v_sub_f32_e32 v93, v141, v236
	v_sub_f32_e32 v110, v126, v236
	v_sub_f32_e32 v94, v142, v236
	v_sub_f32_e32 v111, v127, v236
	v_sub_f32_e32 v95, v143, v236
	ds_read_b64_tr_b16 v[112:113], v0 offset:0x200
	ds_read_b64_tr_b16 v[114:115], v0 offset:0xa00
	ds_read_b64_tr_b16 v[116:117], v0 offset:0x1200
	ds_read_b64_tr_b16 v[118:119], v0 offset:0x1a00
	ds_read_b64_tr_b16 v[120:121], v0 offset:0x2200
	ds_read_b64_tr_b16 v[122:123], v0 offset:0x2a00
	ds_read_b64_tr_b16 v[124:125], v0 offset:0x3200
	ds_read_b64_tr_b16 v[126:127], v0 offset:0x3a00
	s_waitcnt lgkmcnt(8)
	v_mfma_f32_32x32x16_bf16 v[64:79], v[192:195], v[208:211], v[64:79]
	v_exp_f32_e32 v96, v96
	v_exp_f32_e32 v80, v80
	v_mfma_f32_32x32x16_bf16 v[64:79], v[10:13], v[204:207], v[64:79]
	v_exp_f32_e32 v97, v97
	v_exp_f32_e32 v81, v81
	v_mfma_f32_32x32x16_bf16 v[64:79], v[6:9], v[200:203], v[64:79]
	v_exp_f32_e32 v98, v98
	v_exp_f32_e32 v82, v82
	v_mfma_f32_32x32x16_bf16 v[64:79], v[2:5], v[196:199], v[64:79]
	v_exp_f32_e32 v99, v99
	v_exp_f32_e32 v83, v83
	ds_read_b64_tr_b16 v[128:129], v0 offset:0x400
	ds_read_b64_tr_b16 v[130:131], v0 offset:0xc00
	ds_read_b64_tr_b16 v[132:133], v0 offset:0x1400
	ds_read_b64_tr_b16 v[134:135], v0 offset:0x1c00
	ds_read_b64_tr_b16 v[136:137], v0 offset:0x2400
	ds_read_b64_tr_b16 v[138:139], v0 offset:0x2c00
	ds_read_b64_tr_b16 v[140:141], v0 offset:0x3400
	ds_read_b64_tr_b16 v[142:143], v0 offset:0x3c00
	s_waitcnt lgkmcnt(8)
	v_mfma_f32_32x32x16_bf16 v[48:63], v[192:195], v[112:115], v[48:63]
	v_exp_f32_e32 v100, v100
	v_exp_f32_e32 v84, v84
	v_mfma_f32_32x32x16_bf16 v[48:63], v[10:13], v[116:119], v[48:63]
	v_exp_f32_e32 v101, v101
	v_exp_f32_e32 v85, v85
	v_mfma_f32_32x32x16_bf16 v[48:63], v[6:9], v[120:123], v[48:63]
	v_exp_f32_e32 v102, v102
	v_exp_f32_e32 v86, v86
	v_mfma_f32_32x32x16_bf16 v[48:63], v[2:5], v[124:127], v[48:63]
	v_exp_f32_e32 v103, v103
	v_exp_f32_e32 v87, v87
	ds_read_b64_tr_b16 v[112:113], v0 offset:0x600
	ds_read_b64_tr_b16 v[114:115], v0 offset:0xe00
	ds_read_b64_tr_b16 v[116:117], v0 offset:0x1600
	ds_read_b64_tr_b16 v[118:119], v0 offset:0x1e00
	ds_read_b64_tr_b16 v[120:121], v0 offset:0x2600
	ds_read_b64_tr_b16 v[122:123], v0 offset:0x2e00
	ds_read_b64_tr_b16 v[124:125], v0 offset:0x3600
	ds_read_b64_tr_b16 v[126:127], v0 offset:0x3e00
	s_waitcnt lgkmcnt(8)
	v_mfma_f32_32x32x16_bf16 v[32:47], v[192:195], v[128:131], v[32:47]
	v_exp_f32_e32 v104, v104
	v_exp_f32_e32 v88, v88
	v_mfma_f32_32x32x16_bf16 v[32:47], v[10:13], v[132:135], v[32:47]
	v_exp_f32_e32 v105, v105
	v_exp_f32_e32 v89, v89
	v_mfma_f32_32x32x16_bf16 v[32:47], v[6:9], v[136:139], v[32:47]
	v_exp_f32_e32 v106, v106
	v_exp_f32_e32 v90, v90
	v_mfma_f32_32x32x16_bf16 v[32:47], v[2:5], v[140:143], v[32:47]
	v_exp_f32_e32 v107, v107
	v_exp_f32_e32 v91, v91
	s_waitcnt lgkmcnt(0)
	v_mfma_f32_32x32x16_bf16 v[16:31], v[192:195], v[112:115], v[16:31]
	v_exp_f32_e32 v108, v108
	v_exp_f32_e32 v92, v92
	v_mfma_f32_32x32x16_bf16 v[16:31], v[10:13], v[116:119], v[16:31]
	v_exp_f32_e32 v109, v109
	v_exp_f32_e32 v93, v93
	v_mfma_f32_32x32x16_bf16 v[16:31], v[6:9], v[120:123], v[16:31]
	v_exp_f32_e32 v110, v110
	v_exp_f32_e32 v94, v94
	v_mfma_f32_32x32x16_bf16 v[16:31], v[2:5], v[124:127], v[16:31]
	v_exp_f32_e32 v111, v111
	v_exp_f32_e32 v95, v95
	s_branch .Lresc_mla_odd

.Lfm_even_exp:
	v_sub_f32_e32 v96, v112, v236
	v_sub_f32_e32 v80, v128, v236
	v_sub_f32_e32 v97, v113, v236
	v_sub_f32_e32 v81, v129, v236
	v_sub_f32_e32 v98, v114, v236
	v_sub_f32_e32 v82, v130, v236
	v_sub_f32_e32 v99, v115, v236
	v_sub_f32_e32 v83, v131, v236
	v_sub_f32_e32 v100, v116, v236
	v_sub_f32_e32 v84, v132, v236
	v_sub_f32_e32 v101, v117, v236
	v_sub_f32_e32 v85, v133, v236
	v_sub_f32_e32 v102, v118, v236
	v_sub_f32_e32 v86, v134, v236
	v_sub_f32_e32 v103, v119, v236
	v_sub_f32_e32 v87, v135, v236
	v_sub_f32_e32 v104, v120, v236
	v_sub_f32_e32 v88, v136, v236
	v_sub_f32_e32 v105, v121, v236
	v_sub_f32_e32 v89, v137, v236
	v_sub_f32_e32 v106, v122, v236
	v_sub_f32_e32 v90, v138, v236
	v_sub_f32_e32 v107, v123, v236
	v_sub_f32_e32 v91, v139, v236
	v_sub_f32_e32 v108, v124, v236
	v_sub_f32_e32 v92, v140, v236
	v_sub_f32_e32 v109, v125, v236
	v_sub_f32_e32 v93, v141, v236
	v_sub_f32_e32 v110, v126, v236
	v_sub_f32_e32 v94, v142, v236
	v_sub_f32_e32 v111, v127, v236
	v_sub_f32_e32 v95, v143, v236
	ds_read_b64_tr_b16 v[112:113], v243 offset:0x200
	ds_read_b64_tr_b16 v[114:115], v243 offset:0xa00
	ds_read_b64_tr_b16 v[116:117], v243 offset:0x1200
	ds_read_b64_tr_b16 v[118:119], v243 offset:0x1a00
	ds_read_b64_tr_b16 v[120:121], v243 offset:0x2200
	ds_read_b64_tr_b16 v[122:123], v243 offset:0x2a00
	ds_read_b64_tr_b16 v[124:125], v243 offset:0x3200
	ds_read_b64_tr_b16 v[126:127], v243 offset:0x3a00
	s_waitcnt lgkmcnt(8)
	v_mfma_f32_32x32x16_bf16 v[64:79], v[192:195], v[208:211], v[64:79]
	v_exp_f32_e32 v96, v96
	v_exp_f32_e32 v80, v80
	v_mfma_f32_32x32x16_bf16 v[64:79], v[10:13], v[204:207], v[64:79]
	v_exp_f32_e32 v97, v97
	v_exp_f32_e32 v81, v81
	v_mfma_f32_32x32x16_bf16 v[64:79], v[6:9], v[200:203], v[64:79]
	v_exp_f32_e32 v98, v98
	v_exp_f32_e32 v82, v82
	v_mfma_f32_32x32x16_bf16 v[64:79], v[2:5], v[196:199], v[64:79]
	v_exp_f32_e32 v99, v99
	v_exp_f32_e32 v83, v83
	ds_read_b64_tr_b16 v[128:129], v243 offset:0x400
	ds_read_b64_tr_b16 v[130:131], v243 offset:0xc00
	ds_read_b64_tr_b16 v[132:133], v243 offset:0x1400
	ds_read_b64_tr_b16 v[134:135], v243 offset:0x1c00
	ds_read_b64_tr_b16 v[136:137], v243 offset:0x2400
	ds_read_b64_tr_b16 v[138:139], v243 offset:0x2c00
	ds_read_b64_tr_b16 v[140:141], v243 offset:0x3400
	ds_read_b64_tr_b16 v[142:143], v243 offset:0x3c00
	s_waitcnt lgkmcnt(8)
	v_mfma_f32_32x32x16_bf16 v[48:63], v[192:195], v[112:115], v[48:63]
	v_exp_f32_e32 v100, v100
	v_exp_f32_e32 v84, v84
	v_mfma_f32_32x32x16_bf16 v[48:63], v[10:13], v[116:119], v[48:63]
	v_exp_f32_e32 v101, v101
	v_exp_f32_e32 v85, v85
	v_mfma_f32_32x32x16_bf16 v[48:63], v[6:9], v[120:123], v[48:63]
	v_exp_f32_e32 v102, v102
	v_exp_f32_e32 v86, v86
	v_mfma_f32_32x32x16_bf16 v[48:63], v[2:5], v[124:127], v[48:63]
	v_exp_f32_e32 v103, v103
	v_exp_f32_e32 v87, v87
	ds_read_b64_tr_b16 v[112:113], v243 offset:0x600
	ds_read_b64_tr_b16 v[114:115], v243 offset:0xe00
	ds_read_b64_tr_b16 v[116:117], v243 offset:0x1600
	ds_read_b64_tr_b16 v[118:119], v243 offset:0x1e00
	ds_read_b64_tr_b16 v[120:121], v243 offset:0x2600
	ds_read_b64_tr_b16 v[122:123], v243 offset:0x2e00
	ds_read_b64_tr_b16 v[124:125], v243 offset:0x3600
	ds_read_b64_tr_b16 v[126:127], v243 offset:0x3e00
	s_waitcnt lgkmcnt(8)
	v_mfma_f32_32x32x16_bf16 v[32:47], v[192:195], v[128:131], v[32:47]
	v_exp_f32_e32 v104, v104
	v_exp_f32_e32 v88, v88
	v_mfma_f32_32x32x16_bf16 v[32:47], v[10:13], v[132:135], v[32:47]
	v_exp_f32_e32 v105, v105
	v_exp_f32_e32 v89, v89
	v_mfma_f32_32x32x16_bf16 v[32:47], v[6:9], v[136:139], v[32:47]
	v_exp_f32_e32 v106, v106
	v_exp_f32_e32 v90, v90
	v_mfma_f32_32x32x16_bf16 v[32:47], v[2:5], v[140:143], v[32:47]
	v_exp_f32_e32 v107, v107
	v_exp_f32_e32 v91, v91
	s_waitcnt lgkmcnt(0)
	v_mfma_f32_32x32x16_bf16 v[16:31], v[192:195], v[112:115], v[16:31]
	v_exp_f32_e32 v108, v108
	v_exp_f32_e32 v92, v92
	v_mfma_f32_32x32x16_bf16 v[16:31], v[10:13], v[116:119], v[16:31]
	v_exp_f32_e32 v109, v109
	v_exp_f32_e32 v93, v93
	v_mfma_f32_32x32x16_bf16 v[16:31], v[6:9], v[120:123], v[16:31]
	v_exp_f32_e32 v110, v110
	v_exp_f32_e32 v94, v94
	v_mfma_f32_32x32x16_bf16 v[16:31], v[2:5], v[124:127], v[16:31]
	v_exp_f32_e32 v111, v111
	v_exp_f32_e32 v95, v95
	s_branch .Lresc_mla_even
